# MFMA-LDS interleave: uq K-step operand read-ahead deepened from 8 to 12 reads (22-quad ring)
# speedup vs baseline: 1.0002x; 1.0002x over previous
; #define SBAR() __builtin_amdgcn_sched_barrier(0)
; DEV int opaque_tid() { int t = threadIdx.x; asm volatile("" : "+v"(t)); return t; }
; DEV void glds16(const u16* g, char* l) { __builtin_amdgcn_global_load_lds((const unsigned*)g, (unsigned*)l, 16, 0, 0); }
; template <int WM, int WN, int BN, int EPI>
; DEV void gemm_tile(const u16* __restrict__ A, int lda, const u16* __restrict__ Bt, int ldb, int K, int m0, char* lds,
;                    const Params& P, int layer, int batch, int nt) {
;     ...
;   const int tid = opaque_tid(), wid = tid >> 6, lane = tid & 63, r32 = lane & 31, hi = lane >> 5;
;   const int wm = wid / WN, wn = wid % WN;
;   char* As = lds; char* Bs = lds + 65536;
;   f32x16 acc[MI][NI];
; #pragma unroll
;   for (int mi = 0; mi < MI; ++mi)
; #pragma unroll
;     for (int ni = 0; ni < NI; ++ni) acc[mi][ni] = f32x16{};
;   const int srow = tid >> 3, sch = (tid & 7) ^ ((srow >> 1) & 7);
;   const u16* Ap = A + (long)(m0 + srow) * lda + sch * 8;
;   const u16* Bp = Bt + (long)srow * ldb + sch * 8;
;   const int soff = tid * 16;
;     ...
;   GLOAD(0, 0); asm volatile("s_waitcnt vmcnt(0)" ::: "memory"); __syncthreads();
;   const int nk = K >> 6;
;   for (int kt = 0; kt < nk; ++kt) {
;     const bool more = kt + 1 < nk;
;     const int nb = (kt + 1) & 1;
;     const char* as = As + (kt & 1) * 32768; const char* bs = Bs + (kt & 1) * 32768;
; #pragma unroll
;     for (int ks = 0; ks < 4; ++ks) {
;       if (more) { glds16(Ap + (long)ks * 64 * lda + (kt + 1) * 64, As + nb * 32768 + soff + ks * 8192);
;                   if (ks < NB) glds16(Bp + (long)ks * 64 * ldb + (kt + 1) * 64, Bs + nb * 32768 + soff + ks * 8192); }
;       SBAR();
;       bf16x8 xf[MI], wf[NI];
; #pragma unroll
;       for (int mi = 0; mi < MI; ++mi) xf[mi] = *reinterpret_cast<const bf16x8*>(as + swz128(wm * (MI * 32) + mi * 32 + r32, ks * 2 + hi));
; #pragma unroll
;       for (int ni = 0; ni < NI; ++ni) wf[ni] = *reinterpret_cast<const bf16x8*>(bs + swz128(wn * (NI * 32) + ni * 32 + r32, ks * 2 + hi));
; #pragma unroll
;       for (int mi = 0; mi < MI; ++mi)
; #pragma unroll
;         for (int ni = 0; ni < NI; ++ni) acc[mi][ni] = __builtin_amdgcn_mfma_f32_32x32x16_bf16(wf[ni], xf[mi], acc[mi][ni], 0, 0, 0);
;     }
.LBB0_358:
	s_mul_i32 s2, s54, 0xc0
	s_mul_i32 s3, s51, 0x300
	s_add_i32 s3, s2, s3
	s_lshl_b32 s3, s3, 9
	s_add_u32 s60, s36, s3
	s_addc_u32 s61, s38, 0
	s_lshl_b32 s3, s55, 8
	v_mov_b32_e32 v100, v226
	s_and_b32 s3, s3, 0x3f00
	s_add_i32 s22, 0, 0x10000
	v_ashrrev_i32_e32 v0, 3, v100
	v_lshrrev_b32_e32 v1, 4, v100
	v_add_u32_e32 v2, s3, v0
	v_xor_b32_e32 v1, v1, v100
	v_ashrrev_i32_e32 v3, 31, v2
	v_lshlrev_b32_e32 v5, 4, v100
	v_lshlrev_b64 v[2:3], 9, v[2:3]
	v_lshlrev_b32_e32 v1, 4, v1
	v_add_u32_e32 v120, 0, v5
	v_lshl_add_u64 v[2:3], s[6:7], 0, v[2:3]
	v_and_b32_e32 v184, 0x70, v1
	v_readfirstlane_b32 s82, v120
	v_add_u32_e32 v6, 0x2000, v120
	v_lshl_add_u64 v[96:97], v[2:3], 0, v[184:185]
	v_ashrrev_i32_e32 v1, 31, v0
	s_mov_b32 m0, s82
	v_readfirstlane_b32 s79, v6
	v_add_u32_e32 v6, 0x4000, v120
	v_lshlrev_b64 v[0:1], 9, v[0:1]
	global_load_lds_dwordx4 v[96:97], off
	v_lshl_add_u64 v[2:3], v[96:97], 0, s[40:41]
	s_mov_b32 m0, s79
	v_readfirstlane_b32 s65, v6
	v_lshl_add_u64 v[0:1], s[60:61], 0, v[0:1]
	global_load_lds_dwordx4 v[2:3], off
	v_lshl_add_u64 v[2:3], v[96:97], 0, s[28:29]
	s_mov_b32 m0, s65
	s_mov_b64 s[60:61], 0x18000
	v_add_u32_e32 v6, 0x6000, v120
	global_load_lds_dwordx4 v[2:3], off
	v_lshl_add_u64 v[2:3], v[96:97], 0, s[60:61]
	v_readfirstlane_b32 s60, v6
	s_mov_b32 m0, s60
	v_add_u32_e32 v121, s22, v5
	global_load_lds_dwordx4 v[2:3], off
	v_readfirstlane_b32 s81, v121
	v_add_u32_e32 v2, 0x2000, v121
	v_lshl_add_u64 v[98:99], v[0:1], 0, v[184:185]
	s_mov_b32 m0, s81
	v_readfirstlane_b32 s75, v2
	v_add_u32_e32 v2, 0x4000, v121
	global_load_lds_dwordx4 v[98:99], off
	v_lshl_add_u64 v[0:1], v[98:99], 0, s[40:41]
	s_mov_b32 m0, s75
	v_readfirstlane_b32 s61, v2
	v_and_b32_e32 v101, 31, v100
	global_load_lds_dwordx4 v[0:1], off
	v_lshl_add_u64 v[0:1], v[98:99], 0, s[28:29]
	s_mov_b32 m0, s61
	v_add_u32_e32 v5, 0x8000, v120
	v_ashrrev_i32_e32 v103, 6, v100
	global_load_lds_dwordx4 v[0:1], off
	v_lshlrev_b32_e32 v1, 7, v101
	v_add_u32_e32 v6, 0x8000, v121
	v_readfirstlane_b32 s62, v5
	v_lshlrev_b32_e32 v0, 12, v103
	v_add_u32_e32 v124, s22, v1
	v_lshl_add_u64 v[2:3], v[96:97], 0, s[30:31]
	s_mov_b32 m0, s62
	v_readfirstlane_b32 s22, v6
	s_waitcnt vmcnt(0)
	s_waitcnt vmcnt(0) lgkmcnt(0)
	s_barrier
	v_add3_u32 v123, 0, v0, v1
	v_lshl_add_u64 v[0:1], v[98:99], 0, s[30:31]
	global_load_lds_dwordx4 v[2:3], off
	s_mov_b32 m0, s22
	v_lshrrev_b32_e32 v4, 5, v100
	global_load_lds_dwordx4 v[0:1], off
	v_bfe_u32 v102, v100, 5, 1
	v_bfe_u32 v122, v100, 1, 3
	v_bitop3_b32 v0, v4, v122, 1 bitop3:0x6c
	v_lshlrev_b32_e32 v4, 4, v0
	v_add_u32_e32 v104, v124, v4
	ds_read_b128 v[194:197], v104
	v_add_u32_e32 v125, v123, v4
	ds_read_b128 v[198:201], v125
	ds_read_b128 v[202:205], v104 offset:4096
	ds_read_b128 v[206:209], v104 offset:8192
	ds_read_b128 v[210:213], v104 offset:12288
	ds_read_b128 v[214:217], v104 offset:16384
	ds_read_b128 v[218:221], v104 offset:20480
	v_add_u32_e32 v26, 0xa000, v121
	v_lshl_add_u64 v[24:25], v[96:97], 0, s[42:43]
	v_readfirstlane_b32 s63, v26
	s_waitcnt lgkmcnt(5)
	v_mfma_f32_32x32x16_bf16 v[80:95], v[194:197], v[198:201], 0
	s_waitcnt lgkmcnt(3)
	v_mfma_f32_32x32x16_bf16 v[64:79], v[202:205], v[198:201], 0
	v_mfma_f32_32x32x16_bf16 v[48:63], v[206:209], v[198:201], 0
	s_waitcnt lgkmcnt(0)
	v_mfma_f32_32x32x16_bf16 v[32:47], v[210:213], v[198:201], 0
	v_add_u32_e32 v0, 0xa000, v120
	s_nop 0
	v_readfirstlane_b32 s74, v0
	s_mov_b32 m0, s74
	s_nop 0
	global_load_lds_dwordx4 v[24:25], off
	v_lshl_add_u64 v[24:25], v[98:99], 0, s[42:43]
	s_mov_b32 m0, s63
	v_mfma_f32_32x32x16_bf16 v[0:15], v[214:217], v[198:201], 0
	global_load_lds_dwordx4 v[24:25], off
	v_mfma_f32_32x32x16_bf16 v[16:31], v[218:221], v[198:201], 0
	v_bitop3_b32 v105, v102, v122, 2 bitop3:0x36
	v_lshlrev_b32_e32 v110, 4, v105
	v_add_u32_e32 v105, v124, v110
	ds_read_b128 v[222:225], v105
	v_add_u32_e32 v126, v123, v110
	ds_read_b128 v[232:235], v126
	ds_read_b128 v[236:239], v105 offset:4096
	ds_read_b128 v[240:243], v105 offset:8192
	ds_read_b128 v[244:247], v105 offset:12288
	ds_read_b128 v[248:251], v105 offset:16384
	ds_read_b128 v[142:145], v105 offset:20480
	v_add_u32_e32 v127, 0xc000, v120
	s_mov_b64 s[86:87], 0x10080
	v_readfirstlane_b32 s78, v127
	v_lshl_add_u64 v[118:119], v[96:97], 0, s[86:87]
	s_mov_b32 m0, s78
	s_waitcnt lgkmcnt(5)
	v_mfma_f32_32x32x16_bf16 v[80:95], v[222:225], v[232:235], v[80:95]
	s_waitcnt lgkmcnt(3)
	v_mfma_f32_32x32x16_bf16 v[64:79], v[236:239], v[232:235], v[64:79]
	v_mfma_f32_32x32x16_bf16 v[48:63], v[240:243], v[232:235], v[48:63]
	s_waitcnt lgkmcnt(1)
	v_mfma_f32_32x32x16_bf16 v[0:15], v[248:251], v[232:235], v[0:15]
	v_add_u32_e32 v116, 0xc000, v121
	v_lshl_add_u64 v[114:115], v[98:99], 0, s[86:87]
	v_readfirstlane_b32 s64, v116
	v_mfma_f32_32x32x16_bf16 v[32:47], v[244:247], v[232:235], v[32:47]
	global_load_lds_dwordx4 v[118:119], off
	s_mov_b32 m0, s64
	s_nop 0
	global_load_lds_dwordx4 v[114:115], off
	s_waitcnt lgkmcnt(0)
	v_mfma_f32_32x32x16_bf16 v[16:31], v[142:145], v[232:235], v[16:31]
	v_bitop3_b32 v106, v102, v122, 4 bitop3:0x36
	v_lshlrev_b32_e32 v110, 4, v106
	v_add_u32_e32 v118, v124, v110
	ds_read_b128 v[146:149], v118
	v_add_u32_e32 v119, v123, v110
	ds_read_b128 v[150:153], v119
	ds_read_b128 v[154:157], v118 offset:4096
	ds_read_b128 v[158:161], v118 offset:8192
	ds_read_b128 v[162:165], v118 offset:12288
	ds_read_b128 v[166:169], v118 offset:16384
	ds_read_b128 v[170:173], v118 offset:20480
	s_mov_b64 s[86:87], 0x18080
	s_waitcnt lgkmcnt(5)
	v_mfma_f32_32x32x16_bf16 v[80:95], v[146:149], v[150:153], v[80:95]
	s_waitcnt lgkmcnt(3)
; #define SBAR() __builtin_amdgcn_sched_barrier(0)
; DEV void glds16(const u16* g, char* l) { __builtin_amdgcn_global_load_lds((const unsigned*)g, (unsigned*)l, 16, 0, 0); }
; template <int WM, int WN, int BN, int EPI>
; DEV void gemm_tile(const u16* __restrict__ A, int lda, const u16* __restrict__ Bt, int ldb, int K, int m0, char* lds,
;                    const Params& P, int layer, int batch, int nt) {
;     ...
;   for (int kt = 0; kt < nk; ++kt) {
;     const bool more = kt + 1 < nk;
;     const int nb = (kt + 1) & 1;
;     const char* as = As + (kt & 1) * 32768; const char* bs = Bs + (kt & 1) * 32768;
; #pragma unroll
;     for (int ks = 0; ks < 4; ++ks) {
;       if (more) { glds16(Ap + (long)ks * 64 * lda + (kt + 1) * 64, As + nb * 32768 + soff + ks * 8192);
;                   if (ks < NB) glds16(Bp + (long)ks * 64 * ldb + (kt + 1) * 64, Bs + nb * 32768 + soff + ks * 8192); }
;       SBAR();
;       bf16x8 xf[MI], wf[NI];
; #pragma unroll
;       for (int mi = 0; mi < MI; ++mi) xf[mi] = *reinterpret_cast<const bf16x8*>(as + swz128(wm * (MI * 32) + mi * 32 + r32, ks * 2 + hi));
; #pragma unroll
;       for (int ni = 0; ni < NI; ++ni) wf[ni] = *reinterpret_cast<const bf16x8*>(bs + swz128(wn * (NI * 32) + ni * 32 + r32, ks * 2 + hi));
; #pragma unroll
;       for (int mi = 0; mi < MI; ++mi)
; #pragma unroll
;         for (int ni = 0; ni < NI; ++ni) acc[mi][ni] = __builtin_amdgcn_mfma_f32_32x32x16_bf16(wf[ni], xf[mi], acc[mi][ni], 0, 0, 0);
;     }
;     asm volatile("s_waitcnt vmcnt(0)" ::: "memory");
;     __syncthreads();
	v_mfma_f32_32x32x16_bf16 v[64:79], v[154:157], v[150:153], v[64:79]
	v_mfma_f32_32x32x16_bf16 v[48:63], v[158:161], v[150:153], v[48:63]
	s_waitcnt lgkmcnt(1)
	v_mfma_f32_32x32x16_bf16 v[0:15], v[166:169], v[150:153], v[0:15]
	v_add_u32_e32 v116, 0xe000, v120
	v_lshl_add_u64 v[114:115], v[96:97], 0, s[86:87]
	v_readfirstlane_b32 s80, v116
	s_mov_b32 m0, s80
	v_mfma_f32_32x32x16_bf16 v[32:47], v[162:165], v[150:153], v[32:47]
	global_load_lds_dwordx4 v[114:115], off
	s_waitcnt lgkmcnt(0)
	v_mfma_f32_32x32x16_bf16 v[16:31], v[170:173], v[150:153], v[16:31]
	v_bitop3_b32 v106, v102, v122, 6 bitop3:0x36
	v_lshlrev_b32_e32 v110, 4, v106
	v_add_u32_e32 v124, v124, v110
	ds_read_b128 v[174:177], v124
	v_add_u32_e32 v120, v123, v110
	ds_read_b128 v[194:197], v120
	ds_read_b128 v[198:201], v124 offset:4096
	ds_read_b128 v[202:205], v124 offset:8192
	ds_read_b128 v[206:209], v124 offset:12288
	ds_read_b128 v[210:213], v124 offset:16384
	ds_read_b128 v[214:217], v124 offset:20480
	s_mov_b32 m0, s82
	s_mov_b64 s[82:83], 0x100
	s_waitcnt lgkmcnt(5)
	v_mfma_f32_32x32x16_bf16 v[80:95], v[174:177], v[194:197], v[80:95]
	s_waitcnt lgkmcnt(3)
	v_mfma_f32_32x32x16_bf16 v[64:79], v[198:201], v[194:197], v[64:79]
	v_mfma_f32_32x32x16_bf16 v[48:63], v[202:205], v[194:197], v[48:63]
	s_waitcnt lgkmcnt(1)
	v_mfma_f32_32x32x16_bf16 v[0:15], v[210:213], v[194:197], v[0:15]
	v_lshl_add_u64 v[116:117], v[96:97], 0, s[82:83]
	v_lshl_add_u64 v[114:115], v[98:99], 0, s[82:83]
	v_mfma_f32_32x32x16_bf16 v[32:47], v[206:209], v[194:197], v[32:47]
	s_waitcnt vmcnt(0)
	s_waitcnt vmcnt(0) lgkmcnt(0)
	s_barrier
	global_load_lds_dwordx4 v[116:117], off
	s_mov_b32 m0, s81
	v_mfma_f32_32x32x16_bf16 v[16:31], v[214:217], v[194:197], v[16:31]
	global_load_lds_dwordx4 v[114:115], off
	ds_read_b128 v[218:221], v104 offset:32768
	ds_read_b128 v[222:225], v125 offset:32768
	ds_read_b128 v[232:235], v104 offset:36864
	ds_read_b128 v[236:239], v104 offset:40960
	ds_read_b128 v[240:243], v104 offset:45056
	ds_read_b128 v[244:247], v104 offset:49152
	ds_read_b128 v[248:251], v104 offset:53248
	ds_read_b128 v[142:145], v105 offset:32768
	ds_read_b128 v[146:149], v126 offset:32768
	ds_read_b128 v[150:153], v105 offset:36864
	ds_read_b128 v[154:157], v105 offset:40960
	ds_read_b128 v[158:161], v105 offset:45056
	ds_read_b128 v[162:165], v105 offset:49152
	ds_read_b128 v[166:169], v105 offset:53248
	s_mov_b64 s[82:83], 0x8100
	s_mov_b32 m0, s79
	s_waitcnt lgkmcnt(12)
	v_mfma_f32_32x32x16_bf16 v[80:95], v[218:221], v[222:225], v[80:95]
	ds_read_b128 v[170:173], v118 offset:32768
	ds_read_b128 v[174:177], v119 offset:32768
	s_waitcnt lgkmcnt(12)
	v_mfma_f32_32x32x16_bf16 v[64:79], v[232:235], v[222:225], v[64:79]
	v_mfma_f32_32x32x16_bf16 v[48:63], v[236:239], v[222:225], v[48:63]
	ds_read_b128 v[194:197], v118 offset:36864
	ds_read_b128 v[198:201], v118 offset:40960
	s_waitcnt lgkmcnt(12)
	v_mfma_f32_32x32x16_bf16 v[0:15], v[244:247], v[222:225], v[0:15]
	v_lshl_add_u64 v[114:115], v[96:97], 0, s[82:83]
	v_mfma_f32_32x32x16_bf16 v[32:47], v[240:243], v[222:225], v[32:47]
	ds_read_b128 v[202:205], v118 offset:45056
	global_load_lds_dwordx4 v[114:115], off
	v_lshl_add_u64 v[114:115], v[98:99], 0, s[82:83]
	s_mov_b32 m0, s75
	s_nop 0
	global_load_lds_dwordx4 v[114:115], off
	s_waitcnt lgkmcnt(12)
	v_mfma_f32_32x32x16_bf16 v[16:31], v[248:251], v[222:225], v[16:31]
	ds_read_b128 v[206:209], v118 offset:49152
	ds_read_b128 v[210:213], v118 offset:53248
	s_mov_b64 s[82:83], 0x10100
	s_mov_b32 m0, s65
	s_waitcnt lgkmcnt(12)
	v_mfma_f32_32x32x16_bf16 v[80:95], v[142:145], v[146:149], v[80:95]
	ds_read_b128 v[214:217], v124 offset:32768
	ds_read_b128 v[218:221], v120 offset:32768
	s_waitcnt lgkmcnt(12)
	v_mfma_f32_32x32x16_bf16 v[64:79], v[150:153], v[146:149], v[64:79]
	v_mfma_f32_32x32x16_bf16 v[48:63], v[154:157], v[146:149], v[48:63]
	ds_read_b128 v[222:225], v124 offset:36864
	ds_read_b128 v[232:235], v124 offset:40960
	s_waitcnt lgkmcnt(12)
	v_mfma_f32_32x32x16_bf16 v[0:15], v[162:165], v[146:149], v[0:15]
	v_lshl_add_u64 v[114:115], v[96:97], 0, s[82:83]
	v_mfma_f32_32x32x16_bf16 v[32:47], v[158:161], v[146:149], v[32:47]
	ds_read_b128 v[236:239], v124 offset:45056
	global_load_lds_dwordx4 v[114:115], off
	v_lshl_add_u64 v[114:115], v[98:99], 0, s[82:83]
	s_mov_b32 m0, s61
	s_nop 0
	global_load_lds_dwordx4 v[114:115], off
	s_waitcnt lgkmcnt(12)
	v_mfma_f32_32x32x16_bf16 v[16:31], v[166:169], v[146:149], v[16:31]
	ds_read_b128 v[240:243], v124 offset:49152
	ds_read_b128 v[244:247], v124 offset:53248
	s_mov_b32 m0, s60
	s_mov_b64 s[60:61], 0x18100
	s_waitcnt lgkmcnt(12)
	v_mfma_f32_32x32x16_bf16 v[80:95], v[170:173], v[174:177], v[80:95]
	s_waitcnt lgkmcnt(10)
	v_mfma_f32_32x32x16_bf16 v[64:79], v[194:197], v[174:177], v[64:79]
	v_mfma_f32_32x32x16_bf16 v[48:63], v[198:201], v[174:177], v[48:63]
	s_waitcnt lgkmcnt(8)
	v_mfma_f32_32x32x16_bf16 v[0:15], v[206:209], v[174:177], v[0:15]
	v_lshl_add_u64 v[114:115], v[96:97], 0, s[60:61]
	v_mfma_f32_32x32x16_bf16 v[32:47], v[202:205], v[174:177], v[32:47]
	global_load_lds_dwordx4 v[114:115], off
	s_waitcnt lgkmcnt(7)
	v_mfma_f32_32x32x16_bf16 v[16:31], v[210:213], v[174:177], v[16:31]
	s_mov_b64 s[60:61], 0x180
	s_mov_b32 m0, s62
	s_waitcnt lgkmcnt(5)
	v_mfma_f32_32x32x16_bf16 v[80:95], v[214:217], v[218:221], v[80:95]
	s_waitcnt lgkmcnt(3)
	v_mfma_f32_32x32x16_bf16 v[64:79], v[222:225], v[218:221], v[64:79]
	v_mfma_f32_32x32x16_bf16 v[48:63], v[232:235], v[218:221], v[48:63]
	s_waitcnt lgkmcnt(1)
	v_mfma_f32_32x32x16_bf16 v[0:15], v[240:243], v[218:221], v[0:15]
	v_lshl_add_u64 v[116:117], v[96:97], 0, s[60:61]
	v_lshl_add_u64 v[114:115], v[98:99], 0, s[60:61]
	v_mfma_f32_32x32x16_bf16 v[32:47], v[236:239], v[218:221], v[32:47]
	s_waitcnt vmcnt(0)
	s_waitcnt vmcnt(0) lgkmcnt(0)
	s_barrier
; #define SBAR() __builtin_amdgcn_sched_barrier(0)
; DEV void glds16(const u16* g, char* l) { __builtin_amdgcn_global_load_lds((const unsigned*)g, (unsigned*)l, 16, 0, 0); }
; template <int WM, int WN, int BN, int EPI>
; DEV void gemm_tile(const u16* __restrict__ A, int lda, const u16* __restrict__ Bt, int ldb, int K, int m0, char* lds,
;                    const Params& P, int layer, int batch, int nt) {
;     ...
;   for (int kt = 0; kt < nk; ++kt) {
;     const bool more = kt + 1 < nk;
;     const int nb = (kt + 1) & 1;
;     const char* as = As + (kt & 1) * 32768; const char* bs = Bs + (kt & 1) * 32768;
; #pragma unroll
;     for (int ks = 0; ks < 4; ++ks) {
;       if (more) { glds16(Ap + (long)ks * 64 * lda + (kt + 1) * 64, As + nb * 32768 + soff + ks * 8192);
;                   if (ks < NB) glds16(Bp + (long)ks * 64 * ldb + (kt + 1) * 64, Bs + nb * 32768 + soff + ks * 8192); }
;       SBAR();
;       bf16x8 xf[MI], wf[NI];
; #pragma unroll
;       for (int mi = 0; mi < MI; ++mi) xf[mi] = *reinterpret_cast<const bf16x8*>(as + swz128(wm * (MI * 32) + mi * 32 + r32, ks * 2 + hi));
; #pragma unroll
;       for (int ni = 0; ni < NI; ++ni) wf[ni] = *reinterpret_cast<const bf16x8*>(bs + swz128(wn * (NI * 32) + ni * 32 + r32, ks * 2 + hi));
; #pragma unroll
;       for (int mi = 0; mi < MI; ++mi)
; #pragma unroll
;         for (int ni = 0; ni < NI; ++ni) acc[mi][ni] = __builtin_amdgcn_mfma_f32_32x32x16_bf16(wf[ni], xf[mi], acc[mi][ni], 0, 0, 0);
;     }
;     asm volatile("s_waitcnt vmcnt(0)" ::: "memory");
;     __syncthreads();
	global_load_lds_dwordx4 v[116:117], off
	s_mov_b32 m0, s22
	v_mfma_f32_32x32x16_bf16 v[16:31], v[244:247], v[218:221], v[16:31]
	global_load_lds_dwordx4 v[114:115], off
	ds_read_b128 v[248:251], v104
	ds_read_b128 v[142:145], v125
	ds_read_b128 v[146:149], v104 offset:4096
	ds_read_b128 v[150:153], v104 offset:8192
	ds_read_b128 v[154:157], v104 offset:12288
	ds_read_b128 v[158:161], v104 offset:16384
	ds_read_b128 v[162:165], v104 offset:20480
	ds_read_b128 v[166:169], v105
	ds_read_b128 v[170:173], v126
	ds_read_b128 v[174:177], v105 offset:4096
	ds_read_b128 v[194:197], v105 offset:8192
	ds_read_b128 v[198:201], v105 offset:12288
	ds_read_b128 v[202:205], v105 offset:16384
	ds_read_b128 v[206:209], v105 offset:20480
	s_mov_b64 s[60:61], 0x8180
	s_mov_b32 m0, s74
	s_waitcnt lgkmcnt(12)
	v_mfma_f32_32x32x16_bf16 v[80:95], v[248:251], v[142:145], v[80:95]
	ds_read_b128 v[210:213], v118
	ds_read_b128 v[214:217], v119
	s_waitcnt lgkmcnt(12)
	v_mfma_f32_32x32x16_bf16 v[64:79], v[146:149], v[142:145], v[64:79]
	v_mfma_f32_32x32x16_bf16 v[48:63], v[150:153], v[142:145], v[48:63]
	ds_read_b128 v[218:221], v118 offset:4096
	ds_read_b128 v[222:225], v118 offset:8192
	s_waitcnt lgkmcnt(12)
	v_mfma_f32_32x32x16_bf16 v[0:15], v[158:161], v[142:145], v[0:15]
	v_lshl_add_u64 v[114:115], v[96:97], 0, s[60:61]
	v_mfma_f32_32x32x16_bf16 v[32:47], v[154:157], v[142:145], v[32:47]
	ds_read_b128 v[232:235], v118 offset:12288
	global_load_lds_dwordx4 v[114:115], off
	v_lshl_add_u64 v[114:115], v[98:99], 0, s[60:61]
	s_mov_b32 m0, s63
	s_nop 0
	global_load_lds_dwordx4 v[114:115], off
	s_waitcnt lgkmcnt(12)
	v_mfma_f32_32x32x16_bf16 v[16:31], v[162:165], v[142:145], v[16:31]
	ds_read_b128 v[236:239], v118 offset:16384
	ds_read_b128 v[240:243], v118 offset:20480
	s_mov_b64 s[60:61], 0x10180
	s_mov_b32 m0, s78
	v_lshl_add_u64 v[98:99], v[98:99], 0, s[60:61]
	s_waitcnt lgkmcnt(12)
	v_mfma_f32_32x32x16_bf16 v[80:95], v[166:169], v[170:173], v[80:95]
	ds_read_b128 v[244:247], v124
	ds_read_b128 v[248:251], v120
	s_waitcnt lgkmcnt(12)
	v_mfma_f32_32x32x16_bf16 v[64:79], v[174:177], v[170:173], v[64:79]
	v_mfma_f32_32x32x16_bf16 v[48:63], v[194:197], v[170:173], v[48:63]
	ds_read_b128 v[142:145], v124 offset:4096
	ds_read_b128 v[146:149], v124 offset:8192
	s_waitcnt lgkmcnt(12)
	v_mfma_f32_32x32x16_bf16 v[0:15], v[202:205], v[170:173], v[0:15]
	v_lshl_add_u64 v[114:115], v[96:97], 0, s[60:61]
	v_mfma_f32_32x32x16_bf16 v[32:47], v[198:201], v[170:173], v[32:47]
	ds_read_b128 v[150:153], v124 offset:12288
	global_load_lds_dwordx4 v[114:115], off
	s_mov_b32 m0, s64
	s_nop 0
	global_load_lds_dwordx4 v[98:99], off
	s_waitcnt lgkmcnt(12)
	v_mfma_f32_32x32x16_bf16 v[16:31], v[206:209], v[170:173], v[16:31]
	ds_read_b128 v[154:157], v124 offset:16384
	ds_read_b128 v[158:161], v124 offset:20480
	s_mov_b64 s[60:61], 0x18180
	s_mov_b32 m0, s80
	v_lshl_add_u64 v[96:97], v[96:97], 0, s[60:61]
	s_waitcnt lgkmcnt(12)
	v_mfma_f32_32x32x16_bf16 v[80:95], v[210:213], v[214:217], v[80:95]
	s_waitcnt lgkmcnt(10)
	v_mfma_f32_32x32x16_bf16 v[64:79], v[218:221], v[214:217], v[64:79]
	v_mfma_f32_32x32x16_bf16 v[48:63], v[222:225], v[214:217], v[48:63]
	s_waitcnt lgkmcnt(8)
	v_mfma_f32_32x32x16_bf16 v[32:47], v[232:235], v[214:217], v[32:47]
	global_load_lds_dwordx4 v[96:97], off
	v_mfma_f32_32x32x16_bf16 v[0:15], v[236:239], v[214:217], v[0:15]
	s_waitcnt lgkmcnt(7)
	v_mfma_f32_32x32x16_bf16 v[16:31], v[240:243], v[214:217], v[16:31]
	s_waitcnt lgkmcnt(5)
	v_mfma_f32_32x32x16_bf16 v[80:95], v[244:247], v[248:251], v[80:95]
	s_waitcnt lgkmcnt(4)
	v_mfma_f32_32x32x16_bf16 v[64:79], v[142:145], v[248:251], v[64:79]
	s_waitcnt lgkmcnt(3)
	v_mfma_f32_32x32x16_bf16 v[48:63], v[146:149], v[248:251], v[48:63]
	s_waitcnt lgkmcnt(2)
	v_mfma_f32_32x32x16_bf16 v[32:47], v[150:153], v[248:251], v[32:47]
	s_waitcnt lgkmcnt(1)
	v_mfma_f32_32x32x16_bf16 v[0:15], v[154:157], v[248:251], v[0:15]
	s_waitcnt vmcnt(0)
	s_waitcnt vmcnt(0) lgkmcnt(0)
	s_barrier
	v_mfma_f32_32x32x16_bf16 v[16:31], v[158:161], v[248:251], v[16:31]
	ds_read_b128 v[162:165], v104 offset:32768
	ds_read_b128 v[166:169], v125 offset:32768
	ds_read_b128 v[170:173], v104 offset:36864
	ds_read_b128 v[174:177], v104 offset:40960
	ds_read_b128 v[194:197], v104 offset:45056
	ds_read_b128 v[198:201], v104 offset:49152
	ds_read_b128 v[202:205], v104 offset:53248
	ds_read_b128 v[206:209], v105 offset:32768
	ds_read_b128 v[210:213], v126 offset:32768
	ds_read_b128 v[214:217], v105 offset:36864
	ds_read_b128 v[218:221], v105 offset:40960
	ds_read_b128 v[222:225], v105 offset:45056
	ds_read_b128 v[232:235], v105 offset:49152
	ds_read_b128 v[236:239], v105 offset:53248
	s_waitcnt lgkmcnt(12)
	v_mfma_f32_32x32x16_bf16 v[80:95], v[162:165], v[166:169], v[80:95]
	ds_read_b128 v[240:243], v118 offset:32768
	s_waitcnt lgkmcnt(12)
	v_mfma_f32_32x32x16_bf16 v[64:79], v[170:173], v[166:169], v[64:79]
	ds_read_b128 v[244:247], v119 offset:32768
	s_waitcnt lgkmcnt(12)
	v_mfma_f32_32x32x16_bf16 v[48:63], v[174:177], v[166:169], v[48:63]
	ds_read_b128 v[248:251], v118 offset:36864
	s_waitcnt lgkmcnt(12)
	v_mfma_f32_32x32x16_bf16 v[32:47], v[194:197], v[166:169], v[32:47]
	ds_read_b128 v[142:145], v118 offset:40960
	s_waitcnt lgkmcnt(12)
	v_mfma_f32_32x32x16_bf16 v[0:15], v[198:201], v[166:169], v[0:15]
	ds_read_b128 v[146:149], v118 offset:45056
	s_waitcnt lgkmcnt(12)
	v_mfma_f32_32x32x16_bf16 v[16:31], v[202:205], v[166:169], v[16:31]
	ds_read_b128 v[150:153], v118 offset:49152
	ds_read_b128 v[154:157], v118 offset:53248
	s_waitcnt lgkmcnt(12)
	v_mfma_f32_32x32x16_bf16 v[80:95], v[206:209], v[210:213], v[80:95]
	s_waitcnt lgkmcnt(11)
; #define SBAR() __builtin_amdgcn_sched_barrier(0)
; DEV void glds16(const u16* g, char* l) { __builtin_amdgcn_global_load_lds((const unsigned*)g, (unsigned*)l, 16, 0, 0); }
; DEV void epi_uq(f32x16 (&acc)[1][6], const Params& P, int layer, int batch, int m0, int head, int wid, int r32, int hi, char* lds) {
;   const int t = m0 + wid * 32 + r32;
;   const float rc = __builtin_amdgcn_rsqf((WS{P.ws}.ssq_cq()[t] + WS{P.ws}.ssq_cq()[TB + t] + WS{P.ws}.ssq_cq()[2 * TB + t] + WS{P.ws}.ssq_cq()[3 * TB + t]) * (1.f / 256.f) + EPS);
;   float s = 0.f;
; #pragma unroll
;   for (int ni = 0; ni < 6; ++ni)
; #pragma unroll
;     for (int r = 0; r < 16; ++r) { acc[0][ni][r] *= rc; s += acc[0][ni][r] * acc[0][ni][r]; }
; template <int WM, int WN, int BN, int EPI>
; DEV void gemm_tile(const u16* __restrict__ A, int lda, const u16* __restrict__ Bt, int ldb, int K, int m0, char* lds,
;                    const Params& P, int layer, int batch, int nt) {
;     ...
;   for (int kt = 0; kt < nk; ++kt) {
;     const bool more = kt + 1 < nk;
;     const int nb = (kt + 1) & 1;
;     const char* as = As + (kt & 1) * 32768; const char* bs = Bs + (kt & 1) * 32768;
; #pragma unroll
;     for (int ks = 0; ks < 4; ++ks) {
;       if (more) { glds16(Ap + (long)ks * 64 * lda + (kt + 1) * 64, As + nb * 32768 + soff + ks * 8192);
;                   if (ks < NB) glds16(Bp + (long)ks * 64 * ldb + (kt + 1) * 64, Bs + nb * 32768 + soff + ks * 8192); }
;       SBAR();
;       bf16x8 xf[MI], wf[NI];
; #pragma unroll
;       for (int mi = 0; mi < MI; ++mi) xf[mi] = *reinterpret_cast<const bf16x8*>(as + swz128(wm * (MI * 32) + mi * 32 + r32, ks * 2 + hi));
; #pragma unroll
;       for (int ni = 0; ni < NI; ++ni) wf[ni] = *reinterpret_cast<const bf16x8*>(bs + swz128(wn * (NI * 32) + ni * 32 + r32, ks * 2 + hi));
; #pragma unroll
;       for (int mi = 0; mi < MI; ++mi)
; #pragma unroll
;         for (int ni = 0; ni < NI; ++ni) acc[mi][ni] = __builtin_amdgcn_mfma_f32_32x32x16_bf16(wf[ni], xf[mi], acc[mi][ni], 0, 0, 0);
;     }
;     asm volatile("s_waitcnt vmcnt(0)" ::: "memory");
;     __syncthreads();
	v_mfma_f32_32x32x16_bf16 v[64:79], v[214:217], v[210:213], v[64:79]
	s_waitcnt lgkmcnt(10)
	v_mfma_f32_32x32x16_bf16 v[48:63], v[218:221], v[210:213], v[48:63]
	s_waitcnt lgkmcnt(9)
	v_mfma_f32_32x32x16_bf16 v[32:47], v[222:225], v[210:213], v[32:47]
	s_waitcnt lgkmcnt(8)
	v_mfma_f32_32x32x16_bf16 v[0:15], v[232:235], v[210:213], v[0:15]
	s_waitcnt lgkmcnt(7)
	v_mfma_f32_32x32x16_bf16 v[16:31], v[236:239], v[210:213], v[16:31]
	s_waitcnt lgkmcnt(5)
	v_mfma_f32_32x32x16_bf16 v[80:95], v[240:243], v[244:247], v[80:95]
	s_waitcnt lgkmcnt(4)
	v_mfma_f32_32x32x16_bf16 v[64:79], v[248:251], v[244:247], v[64:79]
	s_waitcnt lgkmcnt(3)
	v_mfma_f32_32x32x16_bf16 v[48:63], v[142:145], v[244:247], v[48:63]
	s_waitcnt lgkmcnt(2)
	v_mfma_f32_32x32x16_bf16 v[32:47], v[146:149], v[244:247], v[32:47]
	s_waitcnt lgkmcnt(1)
	v_mfma_f32_32x32x16_bf16 v[0:15], v[150:153], v[244:247], v[0:15]
	s_waitcnt lgkmcnt(0)
	v_mfma_f32_32x32x16_bf16 v[16:31], v[154:157], v[244:247], v[16:31]
	ds_read_b128 v[96:99], v124 offset:32768
	ds_read_b128 v[104:107], v120 offset:32768
	ds_read_b128 v[108:111], v124 offset:36864
	ds_read_b128 v[112:115], v124 offset:40960
	ds_read_b128 v[116:119], v124 offset:45056
	ds_read_b128 v[120:123], v124 offset:49152
	ds_read_b128 v[124:127], v124 offset:53248
	s_waitcnt vmcnt(0)
	s_waitcnt lgkmcnt(5)
	v_mfma_f32_32x32x16_bf16 v[80:95], v[96:99], v[104:107], v[80:95]
	v_lshl_add_u32 v99, v103, 5, s3
	v_or_b32_e32 v96, v99, v101
	v_ashrrev_i32_e32 v97, 31, v96
	s_mov_b32 s3, 0x20000
	s_waitcnt lgkmcnt(0)
	s_barrier
	v_mfma_f32_32x32x16_bf16 v[64:79], v[108:111], v[104:107], v[64:79]
	v_lshl_add_u64 v[108:109], v[96:97], 2, s[8:9]
	v_add_co_u32_e32 v110, vcc, s93, v108
	v_lshlrev_b32_e32 v184, 4, v102
	s_nop 0
	v_addc_co_u32_e32 v111, vcc, 0, v109, vcc
	s_lshl_b32 s22, s2, 1
	v_mfma_f32_32x32x16_bf16 v[48:63], v[112:115], v[104:107], v[48:63]
	v_add_co_u32_e32 v112, vcc, s3, v108
	s_mov_b32 s3, 0x30000
	s_nop 0
	v_addc_co_u32_e32 v113, vcc, 0, v109, vcc
	v_add_co_u32_e32 v114, vcc, s3, v108
	v_mfma_f32_32x32x16_bf16 v[32:47], v[116:119], v[104:107], v[32:47]
	s_nop 0
	v_addc_co_u32_e32 v115, vcc, 0, v109, vcc
	flat_load_dword v97, v[108:109]
	flat_load_dword v98, v[110:111]
	s_nop 0
	flat_load_dword v108, v[112:113]
	flat_load_dword v109, v[114:115]
	s_movk_i32 s3, 0xfff
	s_waitcnt vmcnt(0) lgkmcnt(0)
	v_add_f32_e32 v97, v97, v98
	v_add_f32_e32 v97, v97, v108
	v_add_f32_e32 v97, v97, v109
	v_fmamk_f32 v97, v97, 0x3b800000, v227
	v_rsq_f32_e32 v98, v97
	v_mfma_f32_32x32x16_bf16 v[0:15], v[120:123], v[104:107], v[0:15]
	v_mul_f32_e32 v108, v81, v98
	v_mul_f32_e32 v97, v80, v98
	v_mul_f32_e32 v113, v86, v98
	v_mul_f32_e32 v86, v108, v108
	v_mul_f32_e32 v109, v82, v98
	v_fmac_f32_e32 v86, v97, v97
	v_mul_f32_e32 v110, v83, v98
	v_fmac_f32_e32 v86, v109, v109
	v_mul_f32_e32 v111, v84, v98
	v_fmac_f32_e32 v86, v110, v110
	v_mul_f32_e32 v112, v85, v98
	v_fmac_f32_e32 v86, v111, v111
	v_fmac_f32_e32 v86, v112, v112
	v_mul_f32_e32 v114, v87, v98
	v_fmac_f32_e32 v86, v113, v113
	v_mul_f32_e32 v115, v88, v98
	v_fmac_f32_e32 v86, v114, v114
	v_mul_f32_e32 v116, v89, v98
	v_fmac_f32_e32 v86, v115, v115
	v_mul_f32_e32 v117, v90, v98
	v_fmac_f32_e32 v86, v116, v116
	v_mul_f32_e32 v118, v91, v98
	v_fmac_f32_e32 v86, v117, v117
	v_mul_f32_e32 v119, v92, v98
	v_fmac_f32_e32 v86, v118, v118
	v_mul_f32_e32 v120, v93, v98
	v_fmac_f32_e32 v86, v119, v119
	v_mul_f32_e32 v121, v94, v98
	v_fmac_f32_e32 v86, v120, v120
	v_mul_f32_e32 v122, v95, v98
	v_fmac_f32_e32 v86, v121, v121
	v_mul_f32_e32 v123, v64, v98
	v_fmac_f32_e32 v86, v122, v122
	v_mfma_f32_32x32x16_bf16 v[16:31], v[124:127], v[104:107], v[16:31]
	v_mul_f32_e32 v124, v65, v98
	v_fmac_f32_e32 v86, v123, v123
	v_mul_f32_e32 v125, v66, v98
	v_fmac_f32_e32 v86, v124, v124
	v_mul_f32_e32 v126, v67, v98
	v_fmac_f32_e32 v86, v125, v125
	v_mul_f32_e32 v127, v68, v98
	v_fmac_f32_e32 v86, v126, v126
	v_mul_f32_e32 v128, v69, v98
	v_fmac_f32_e32 v86, v127, v127
	v_mul_f32_e32 v129, v70, v98
	v_fmac_f32_e32 v86, v128, v128
	v_mul_f32_e32 v130, v71, v98
	v_fmac_f32_e32 v86, v129, v129
	v_mul_f32_e32 v80, v72, v98
	v_fmac_f32_e32 v86, v130, v130
	v_mul_f32_e32 v81, v73, v98
	v_fmac_f32_e32 v86, v80, v80
	v_mul_f32_e32 v82, v74, v98
	v_fmac_f32_e32 v86, v81, v81
	v_mul_f32_e32 v83, v75, v98
	v_fmac_f32_e32 v86, v82, v82
	v_mul_f32_e32 v72, v76, v98
	v_fmac_f32_e32 v86, v83, v83
	v_mul_f32_e32 v73, v77, v98
	v_fmac_f32_e32 v86, v72, v72
	v_mul_f32_e32 v74, v78, v98
	v_fmac_f32_e32 v86, v73, v73
	v_mul_f32_e32 v75, v79, v98
	v_fmac_f32_e32 v86, v74, v74
	v_mul_f32_e32 v131, v36, v98
	v_mul_f32_e32 v132, v37, v98
	v_lshl_add_u64 v[36:37], s[10:11], 0, v[184:185]
	v_mul_f32_e32 v68, v48, v98
	v_mul_f32_e32 v70, v50, v98
	v_mul_f32_e32 v71, v51, v98
	v_mul_f32_e32 v66, v54, v98
	v_mul_f32_e32 v67, v55, v98
	v_mul_f32_e32 v54, v56, v98
	v_mul_f32_e32 v55, v57, v98
	v_mul_f32_e32 v56, v58, v98
	v_mul_f32_e32 v57, v59, v98
	v_mul_f32_e32 v50, v60, v98
	v_mul_f32_e32 v51, v61, v98
	v_fmac_f32_e32 v86, v75, v75
	flat_load_dwordx4 v[58:61], v[36:37] offset:1280
	global_load_dwordx4 v[194:197], v[36:37], off offset:1312
	global_load_dwordx4 v[198:201], v[36:37], off offset:1344
	global_load_dwordx4 v[202:205], v[36:37], off offset:1376
	global_load_dwordx4 v[206:209], v[36:37], off offset:1408
	global_load_dwordx4 v[210:213], v[36:37], off offset:1440
	global_load_dwordx4 v[214:217], v[36:37], off offset:1472
	global_load_dwordx4 v[218:221], v[36:37], off offset:1504
	global_load_dwordx4 v[222:225], v[36:37], off offset:1536
	global_load_dwordx4 v[232:235], v[36:37], off offset:1568
	global_load_dwordx4 v[236:239], v[36:37], off offset:1600
; DEV void epi_uq(f32x16 (&acc)[1][6], const Params& P, int layer, int batch, int m0, int head, int wid, int r32, int hi, char* lds) {
;     ...
;   const float rc = __builtin_amdgcn_rsqf((WS{P.ws}.ssq_cq()[t] + WS{P.ws}.ssq_cq()[TB + t] + WS{P.ws}.ssq_cq()[2 * TB + t] + WS{P.ws}.ssq_cq()[3 * TB + t]) * (1.f / 256.f) + EPS);
;   float s = 0.f;
; #pragma unroll
;   for (int ni = 0; ni < 6; ++ni)
; #pragma unroll
;     for (int r = 0; r < 16; ++r) { acc[0][ni][r] *= rc; s += acc[0][ni][r] * acc[0][ni][r]; }
;   s = swapsum(s);
;   constexpr float SCQ = 0.07216878364870323f * LOG2E;
;   const float inv = __builtin_amdgcn_rsqf(s * (1.f / 192.f) + EPS) * SCQ;
;   const float* g = WS{P.ws}.consts() + layer * 1024 + 320;
;   char* slab = lds + wid * 12800; char* dst = slab + r32 * 400;
	global_load_dwordx4 v[240:243], v[36:37], off offset:1632
	global_load_dwordx4 v[244:247], v[36:37], off offset:1664
	global_load_dwordx4 v[248:251], v[36:37], off offset:1696
	global_load_dwordx4 v[170:173], v[36:37], off offset:1728
	global_load_dwordx4 v[174:177], v[36:37], off offset:1760
	v_mul_f32_e32 v69, v49, v98
	v_fmac_f32_e32 v86, v68, v68
	v_fmac_f32_e32 v86, v69, v69
	v_fmac_f32_e32 v86, v70, v70
	v_mul_f32_e32 v64, v52, v98
	v_fmac_f32_e32 v86, v71, v71
	v_mul_f32_e32 v65, v53, v98
	v_fmac_f32_e32 v86, v64, v64
	v_fmac_f32_e32 v86, v65, v65
	v_fmac_f32_e32 v86, v66, v66
	v_fmac_f32_e32 v86, v67, v67
	v_fmac_f32_e32 v86, v54, v54
	v_fmac_f32_e32 v86, v55, v55
	v_fmac_f32_e32 v86, v56, v56
	v_fmac_f32_e32 v86, v57, v57
	v_fmac_f32_e32 v86, v50, v50
	v_mul_f32_e32 v52, v62, v98
	v_fmac_f32_e32 v86, v51, v51
	v_mul_f32_e32 v53, v63, v98
	v_fmac_f32_e32 v86, v52, v52
	v_mul_f32_e32 v48, v32, v98
	v_fmac_f32_e32 v86, v53, v53
	v_mul_f32_e32 v33, v33, v98
	v_fmac_f32_e32 v86, v48, v48
	v_mul_f32_e32 v49, v34, v98
	v_fmac_f32_e32 v86, v33, v33
	v_mul_f32_e32 v35, v35, v98
	v_fmac_f32_e32 v86, v49, v49
	v_fmac_f32_e32 v86, v35, v35
	v_fmac_f32_e32 v86, v131, v131
	v_fmac_f32_e32 v86, v132, v132
	v_mul_f32_e32 v133, v38, v98
	v_fmac_f32_e32 v86, v133, v133
	v_mul_f32_e32 v134, v39, v98
	v_fmac_f32_e32 v86, v134, v134
	v_mul_f32_e32 v135, v40, v98
	v_fmac_f32_e32 v86, v135, v135
	v_mul_f32_e32 v136, v41, v98
	v_fmac_f32_e32 v86, v136, v136
	v_mul_f32_e32 v137, v42, v98
	v_fmac_f32_e32 v86, v137, v137
	v_mul_f32_e32 v138, v43, v98
	v_fmac_f32_e32 v86, v138, v138
	v_mul_f32_e32 v139, v44, v98
	v_fmac_f32_e32 v86, v139, v139
	v_mul_f32_e32 v140, v45, v98
	v_mul_f32_e32 v34, v14, v98
	v_mul_lo_u32 v14, v103, s99
	v_fmac_f32_e32 v86, v140, v140
	v_mul_f32_e32 v141, v46, v98
	v_mul_f32_e32 v32, v15, v98
	v_add_u32_e32 v46, 0, v14
	v_mov_b32_e32 v14, v2
	v_mov_b32_e32 v15, v18
	v_mov_b32_e32 v18, v3
	v_mov_b32_e32 v2, v0
	v_mov_b32_e32 v3, v16
	v_fmac_f32_e32 v86, v141, v141
	v_mul_f32_e32 v47, v47, v98
	v_pk_mul_f32 v[42:43], v[2:3], v[98:99] op_sel_hi:[1,0]
	v_mov_b32_e32 v16, v1
	v_fmac_f32_e32 v86, v47, v47
	v_pk_mul_f32 v[84:85], v[42:43], v[42:43]
	v_pk_mul_f32 v[44:45], v[16:17], v[98:99] op_sel_hi:[1,0]
	v_pk_mul_f32 v[14:15], v[14:15], v[98:99] op_sel_hi:[1,0]
	v_add_f32_e32 v0, v84, v86
	v_pk_mul_f32 v[86:87], v[44:45], v[44:45]
	v_pk_mul_f32 v[76:77], v[14:15], v[14:15]
	v_pk_mul_f32 v[40:41], v[18:19], v[98:99] op_sel_hi:[1,0]
	v_add_f32_e32 v0, v86, v0
	v_pk_mul_f32 v[78:79], v[40:41], v[40:41]
	v_add_f32_e32 v0, v76, v0
	v_add_f32_e32 v16, v78, v0
	v_mov_b32_e32 v0, v6
	v_mov_b32_e32 v1, v22
	v_mov_b32_e32 v22, v7
	v_mov_b32_e32 v6, v4
	v_mov_b32_e32 v7, v20
	v_pk_mul_f32 v[6:7], v[6:7], v[98:99] op_sel_hi:[1,0]
	v_mov_b32_e32 v20, v5
	v_pk_mul_f32 v[92:93], v[6:7], v[6:7]
	v_pk_mul_f32 v[4:5], v[20:21], v[98:99] op_sel_hi:[1,0]
	v_pk_mul_f32 v[0:1], v[0:1], v[98:99] op_sel_hi:[1,0]
	v_add_f32_e32 v16, v92, v16
	v_pk_mul_f32 v[20:21], v[4:5], v[4:5]
	v_pk_mul_f32 v[88:89], v[0:1], v[0:1]
	v_pk_mul_f32 v[2:3], v[22:23], v[98:99] op_sel_hi:[1,0]
	v_add_f32_e32 v16, v20, v16
	v_pk_mul_f32 v[90:91], v[2:3], v[2:3]
	v_add_f32_e32 v16, v88, v16
	v_add_f32_e32 v18, v90, v16
	v_mov_b32_e32 v16, v10
	v_mov_b32_e32 v17, v26
	v_pk_mul_f32 v[22:23], v[16:17], v[98:99] op_sel_hi:[1,0]
	v_mov_b32_e32 v16, v8
	v_mov_b32_e32 v17, v24
	v_pk_mul_f32 v[38:39], v[16:17], v[98:99] op_sel_hi:[1,0]
	v_mov_b32_e32 v24, v9
	v_pk_mul_f32 v[104:105], v[38:39], v[38:39]
	v_pk_mul_f32 v[24:25], v[24:25], v[98:99] op_sel_hi:[1,0]
	v_mov_b32_e32 v26, v11
	v_add_f32_e32 v16, v104, v18
	v_pk_mul_f32 v[8:9], v[24:25], v[24:25]
	v_pk_mul_f32 v[94:95], v[22:23], v[22:23]
	v_pk_mul_f32 v[26:27], v[26:27], v[98:99] op_sel_hi:[1,0]
	v_add_f32_e32 v8, v8, v16
	v_mov_b32_e32 v16, v12
	v_mov_b32_e32 v17, v28
	v_pk_mul_f32 v[10:11], v[26:27], v[26:27]
	v_add_f32_e32 v8, v94, v8
	v_pk_mul_f32 v[16:17], v[16:17], v[98:99] op_sel_hi:[1,0]
	v_mov_b32_e32 v28, v13
	v_add_f32_e32 v8, v10, v8
	v_pk_mul_f32 v[106:107], v[16:17], v[16:17]
	v_pk_mul_f32 v[18:19], v[28:29], v[98:99] op_sel_hi:[1,0]
	v_add_f32_e32 v8, v106, v8
	v_pk_mul_f32 v[12:13], v[18:19], v[18:19]
	v_pk_mul_f32 v[30:31], v[30:31], v[98:99] op_sel_hi:[1,0]
	v_add_f32_e32 v8, v12, v8
	v_fmac_f32_e32 v8, v34, v34
	v_fmac_f32_e32 v8, v32, v32
	v_add_f32_e32 v8, v85, v8
	v_add_f32_e32 v8, v87, v8
	v_add_f32_e32 v8, v77, v8
	v_add_f32_e32 v8, v79, v8
	v_add_f32_e32 v8, v93, v8
	v_add_f32_e32 v8, v21, v8
	v_add_f32_e32 v8, v89, v8
	v_add_f32_e32 v8, v91, v8
	v_add_f32_e32 v8, v105, v8
	v_add_f32_e32 v8, v9, v8
	v_add_f32_e32 v8, v95, v8
	v_add_f32_e32 v8, v11, v8
	v_add_f32_e32 v8, v107, v8
	v_pk_mul_f32 v[62:63], v[30:31], v[30:31]
	v_add_f32_e32 v8, v13, v8
	v_add_f32_e32 v8, v62, v8
	v_add_f32_e32 v8, v63, v8
	v_mov_b32_e32 v9, v8
	s_nop 1
	v_permlane32_swap_b32_e32 v8, v9
	v_add_f32_e32 v8, v8, v9
	v_fmamk_f32 v8, v8, 0x3baaaaab, v227
	v_rsq_f32_e32 v8, v8
	v_mul_u32_u24_e32 v9, 0x190, v101
	v_lshlrev_b32_e32 v10, 3, v102
	v_add3_u32 v21, v46, v9, v10
	v_mul_f32_e32 v20, 0x3dd53b94, v8
	v_mul_f32_e32 v8, v97, v20
	v_mul_f32_e32 v9, v108, v20
	s_waitcnt vmcnt(0) lgkmcnt(0)
; DEV void epi_uq(f32x16 (&acc)[1][6], const Params& P, int layer, int batch, int m0, int head, int wid, int r32, int hi, char* lds) {
;     ...
; #pragma unroll
;   for (int ni = 0; ni < 4; ++ni)
; #pragma unroll
;     for (int r4 = 0; r4 < 4; ++r4) {
;       const int c = ni * 32 + r4 * 8 + hi * 4;
;       const float4 gg = *reinterpret_cast<const float4*>(g + c);
;       const f32x16& a = acc[0][ni];
;       st4lds(dst, c, a[r4 * 4] * inv * gg.x, a[r4 * 4 + 1] * inv * gg.y, a[r4 * 4 + 2] * inv * gg.z, a[r4 * 4 + 3] * inv * gg.w);
;     }
	v_mul_f32_e32 v8, v58, v8
	v_mul_f32_e32 v9, v59, v9
	v_mul_f32_e32 v10, v109, v20
	v_mul_f32_e32 v11, v110, v20
	v_mul_f32_e32 v10, v60, v10
	v_mul_f32_e32 v11, v61, v11
	v_cvt_pk_bf16_f32 v8, v8, v9
	v_cvt_pk_bf16_f32 v9, v10, v11
	ds_write_b64 v21, v[8:9]
	v_mul_f32_e32 v12, v111, v20
	v_mul_f32_e32 v13, v116, v20
	v_mul_f32_e32 v28, v117, v20
	v_mul_f32_e32 v29, v118, v20
	v_lshlrev_b32_e32 v184, 5, v102
	v_pk_mul_f32 v[14:15], v[14:15], v[20:21] op_sel_hi:[1,0]
	v_pk_mul_f32 v[40:41], v[40:41], v[20:21] op_sel_hi:[1,0]
	v_pk_mul_f32 v[6:7], v[6:7], v[20:21] op_sel_hi:[1,0]
	v_pk_mul_f32 v[4:5], v[4:5], v[20:21] op_sel_hi:[1,0]
	v_pk_mul_f32 v[0:1], v[0:1], v[20:21] op_sel_hi:[1,0]
	v_pk_mul_f32 v[2:3], v[2:3], v[20:21] op_sel_hi:[1,0]
	v_pk_mul_f32 v[38:39], v[38:39], v[20:21] op_sel_hi:[1,0]
	v_pk_mul_f32 v[24:25], v[24:25], v[20:21] op_sel_hi:[1,0]
	v_pk_mul_f32 v[22:23], v[22:23], v[20:21] op_sel_hi:[1,0]
	v_pk_mul_f32 v[26:27], v[26:27], v[20:21] op_sel_hi:[1,0]
	v_pk_mul_f32 v[16:17], v[16:17], v[20:21] op_sel_hi:[1,0]
	v_pk_mul_f32 v[18:19], v[18:19], v[20:21] op_sel_hi:[1,0]
	s_waitcnt vmcnt(0) lgkmcnt(0)
	v_mul_f32_e32 v8, v194, v12
	v_mul_f32_e32 v12, v112, v20
	v_mul_f32_e32 v9, v12, v195
	v_mul_f32_e32 v12, v113, v20
	v_mul_f32_e32 v10, v12, v196
	v_mul_f32_e32 v12, v114, v20
	v_mul_f32_e32 v11, v12, v197
	v_cvt_pk_bf16_f32 v8, v8, v9
	v_cvt_pk_bf16_f32 v9, v10, v11
	ds_write_b64 v21, v[8:9] offset:16
	v_mul_f32_e32 v12, v115, v20
	s_waitcnt vmcnt(0) lgkmcnt(0)
	v_mul_f32_e32 v8, v12, v198
	v_mul_f32_e32 v9, v13, v199
	v_mul_f32_e32 v10, v28, v200
	v_mul_f32_e32 v11, v29, v201
	v_cvt_pk_bf16_f32 v8, v8, v9
	v_cvt_pk_bf16_f32 v9, v10, v11
	ds_write_b64 v21, v[8:9] offset:32
	v_mul_f32_e32 v12, v119, v20
	v_mul_f32_e32 v13, v120, v20
	v_mul_f32_e32 v28, v121, v20
	v_mul_f32_e32 v29, v122, v20
	s_waitcnt vmcnt(0) lgkmcnt(0)
	v_mul_f32_e32 v8, v12, v202
	v_mul_f32_e32 v9, v13, v203
	v_mul_f32_e32 v10, v28, v204
	v_mul_f32_e32 v11, v29, v205
	v_cvt_pk_bf16_f32 v8, v8, v9
	v_cvt_pk_bf16_f32 v9, v10, v11
	ds_write_b64 v21, v[8:9] offset:48
	v_mul_f32_e32 v12, v123, v20
	v_mul_f32_e32 v13, v124, v20
	v_mul_f32_e32 v28, v125, v20
	v_mul_f32_e32 v29, v126, v20
	s_waitcnt vmcnt(0) lgkmcnt(0)
	v_mul_f32_e32 v8, v12, v206
	v_mul_f32_e32 v9, v13, v207
	v_mul_f32_e32 v10, v28, v208
	v_mul_f32_e32 v11, v29, v209
	v_cvt_pk_bf16_f32 v8, v8, v9
	v_cvt_pk_bf16_f32 v9, v10, v11
	ds_write_b64 v21, v[8:9] offset:64
	v_mul_f32_e32 v12, v127, v20
	v_mul_f32_e32 v13, v128, v20
	v_mul_f32_e32 v28, v129, v20
	v_mul_f32_e32 v29, v130, v20
	s_waitcnt vmcnt(0) lgkmcnt(0)
	v_mul_f32_e32 v8, v12, v210
	v_mul_f32_e32 v9, v13, v211
	v_mul_f32_e32 v10, v28, v212
	v_mul_f32_e32 v11, v29, v213
	v_cvt_pk_bf16_f32 v8, v8, v9
	v_cvt_pk_bf16_f32 v9, v10, v11
	ds_write_b64 v21, v[8:9] offset:80
	v_mul_f32_e32 v12, v80, v20
	v_mul_f32_e32 v13, v81, v20
	v_mul_f32_e32 v28, v82, v20
	v_mul_f32_e32 v29, v83, v20
	s_waitcnt vmcnt(0) lgkmcnt(0)
	v_mul_f32_e32 v8, v12, v214
	v_mul_f32_e32 v9, v13, v215
	v_mul_f32_e32 v10, v28, v216
	v_mul_f32_e32 v11, v29, v217
	v_cvt_pk_bf16_f32 v8, v8, v9
	v_cvt_pk_bf16_f32 v9, v10, v11
	ds_write_b64 v21, v[8:9] offset:96
	v_mul_f32_e32 v12, v72, v20
	v_mul_f32_e32 v13, v73, v20
	v_mul_f32_e32 v28, v74, v20
	v_mul_f32_e32 v29, v75, v20
	s_waitcnt vmcnt(0) lgkmcnt(0)
	v_mul_f32_e32 v8, v12, v218
	v_mul_f32_e32 v9, v13, v219
	v_mul_f32_e32 v10, v28, v220
	v_mul_f32_e32 v11, v29, v221
	v_cvt_pk_bf16_f32 v8, v8, v9
	v_cvt_pk_bf16_f32 v9, v10, v11
	ds_write_b64 v21, v[8:9] offset:112
	v_mul_f32_e32 v12, v68, v20
	v_mul_f32_e32 v13, v69, v20
	v_mul_f32_e32 v28, v70, v20
	v_mul_f32_e32 v29, v71, v20
	s_waitcnt vmcnt(0) lgkmcnt(0)
	v_mul_f32_e32 v8, v12, v222
	v_mul_f32_e32 v9, v13, v223
	v_mul_f32_e32 v10, v28, v224
	v_mul_f32_e32 v11, v29, v225
	v_cvt_pk_bf16_f32 v8, v8, v9
	v_cvt_pk_bf16_f32 v9, v10, v11
	ds_write_b64 v21, v[8:9] offset:128
	v_mul_f32_e32 v12, v64, v20
	v_mul_f32_e32 v13, v65, v20
	v_mul_f32_e32 v28, v66, v20
	v_mul_f32_e32 v29, v67, v20
	s_waitcnt vmcnt(0) lgkmcnt(0)
	v_mul_f32_e32 v8, v12, v232
	v_mul_f32_e32 v9, v13, v233
	v_mul_f32_e32 v10, v28, v234
	v_mul_f32_e32 v11, v29, v235
	v_cvt_pk_bf16_f32 v8, v8, v9
	v_cvt_pk_bf16_f32 v9, v10, v11
	ds_write_b64 v21, v[8:9] offset:144
	v_mul_f32_e32 v12, v54, v20
	v_mul_f32_e32 v13, v55, v20
	v_mul_f32_e32 v28, v56, v20
	v_mul_f32_e32 v29, v57, v20
	s_waitcnt vmcnt(0) lgkmcnt(0)
	v_mul_f32_e32 v8, v12, v236
	v_mul_f32_e32 v9, v13, v237
	v_mul_f32_e32 v10, v28, v238
	v_mul_f32_e32 v11, v29, v239
	v_cvt_pk_bf16_f32 v8, v8, v9
	v_cvt_pk_bf16_f32 v9, v10, v11
	ds_write_b64 v21, v[8:9] offset:160
	v_mul_f32_e32 v12, v50, v20
	v_mul_f32_e32 v13, v51, v20
	v_mul_f32_e32 v28, v52, v20
	v_mul_f32_e32 v29, v53, v20
	s_waitcnt vmcnt(0) lgkmcnt(0)
	v_mul_f32_e32 v8, v12, v240
	v_mul_f32_e32 v9, v13, v241
	v_mul_f32_e32 v10, v28, v242
	v_mul_f32_e32 v11, v29, v243
	v_cvt_pk_bf16_f32 v8, v8, v9
	v_cvt_pk_bf16_f32 v9, v10, v11
	ds_write_b64 v21, v[8:9] offset:176
	v_mul_f32_e32 v12, v48, v20
	v_mul_f32_e32 v13, v33, v20
	v_mul_f32_e32 v28, v49, v20
	v_mul_f32_e32 v29, v35, v20
	s_waitcnt vmcnt(0) lgkmcnt(0)
	v_mul_f32_e32 v8, v12, v244
	v_mul_f32_e32 v9, v13, v245
	v_mul_f32_e32 v10, v28, v246
	v_mul_f32_e32 v11, v29, v247
	v_cvt_pk_bf16_f32 v8, v8, v9
	v_cvt_pk_bf16_f32 v9, v10, v11
	ds_write_b64 v21, v[8:9] offset:192
	v_mul_f32_e32 v12, v131, v20
	v_mul_f32_e32 v13, v132, v20
	v_mul_f32_e32 v28, v133, v20
	v_mul_f32_e32 v29, v134, v20
	s_waitcnt vmcnt(0) lgkmcnt(0)
; DEV void epi_uq(f32x16 (&acc)[1][6], const Params& P, int layer, int batch, int m0, int head, int wid, int r32, int hi, char* lds) {
;     ...
; #pragma unroll
;   for (int ni = 0; ni < 4; ++ni)
; #pragma unroll
;     for (int r4 = 0; r4 < 4; ++r4) {
;       const int c = ni * 32 + r4 * 8 + hi * 4;
;       const float4 gg = *reinterpret_cast<const float4*>(g + c);
;       const f32x16& a = acc[0][ni];
;       st4lds(dst, c, a[r4 * 4] * inv * gg.x, a[r4 * 4 + 1] * inv * gg.y, a[r4 * 4 + 2] * inv * gg.z, a[r4 * 4 + 3] * inv * gg.w);
;     }
;   const int pos = batch ? t : (t & 4095);
;   const float2* rp = WS{P.ws}.rope() + (long)pos * 32;
; #pragma unroll
;   for (int r4 = 0; r4 < 4; ++r4) {
;     const int i = r4 * 8 + hi * 4;
;     const float4 g1 = *reinterpret_cast<const float4*>(g + 128 + i), g2 = *reinterpret_cast<const float4*>(g + 160 + i);
;     const float4 cs01 = *reinterpret_cast<const float4*>(rp + i), cs23 = *reinterpret_cast<const float4*>(rp + i + 2);
;     const float x1[4] = {acc[0][4][r4 * 4] * inv * g1.x, acc[0][4][r4 * 4 + 1] * inv * g1.y, acc[0][4][r4 * 4 + 2] * inv * g1.z, acc[0][4][r4 * 4 + 3] * inv * g1.w};
;     const float x2[4] = {acc[0][5][r4 * 4] * inv * g2.x, acc[0][5][r4 * 4 + 1] * inv * g2.y, acc[0][5][r4 * 4 + 2] * inv * g2.z, acc[0][5][r4 * 4 + 3] * inv * g2.w};
;     const float cc[4] = {cs01.x, cs01.z, cs23.x, cs23.z}, sn[4] = {cs01.y, cs01.w, cs23.y, cs23.w};
;     st4lds(dst, 128 + i, x1[0] * cc[0] - x2[0] * sn[0], x1[1] * cc[1] - x2[1] * sn[1], x1[2] * cc[2] - x2[2] * sn[2], x1[3] * cc[3] - x2[3] * sn[3]);
;     st4lds(dst, 160 + i, x1[0] * sn[0] + x2[0] * cc[0], x1[1] * sn[1] + x2[1] * cc[1], x1[2] * sn[2] + x2[2] * cc[2], x1[3] * sn[3] + x2[3] * cc[3]);
;   }
	v_mul_f32_e32 v8, v12, v248
	v_mul_f32_e32 v9, v13, v249
	v_mul_f32_e32 v10, v28, v250
	v_mul_f32_e32 v11, v29, v251
	v_cvt_pk_bf16_f32 v8, v8, v9
	v_cvt_pk_bf16_f32 v9, v10, v11
	ds_write_b64 v21, v[8:9] offset:208
	v_mul_f32_e32 v12, v135, v20
	v_mul_f32_e32 v13, v136, v20
	v_mul_f32_e32 v28, v137, v20
	v_mul_f32_e32 v29, v138, v20
	s_waitcnt vmcnt(0) lgkmcnt(0)
	v_mul_f32_e32 v8, v12, v170
	v_mul_f32_e32 v9, v13, v171
	v_mul_f32_e32 v10, v28, v172
	v_mul_f32_e32 v11, v29, v173
	v_cvt_pk_bf16_f32 v8, v8, v9
	v_cvt_pk_bf16_f32 v9, v10, v11
	ds_write_b64 v21, v[8:9] offset:224
	v_mul_f32_e32 v12, v139, v20
	v_mul_f32_e32 v13, v140, v20
	v_mul_f32_e32 v28, v141, v20
	v_mul_f32_e32 v29, v47, v20
	s_waitcnt vmcnt(0) lgkmcnt(0)
	v_mul_f32_e32 v8, v12, v174
	v_bitop3_b32 v12, v99, s3, v101 bitop3:0xc8
	v_cndmask_b32_e64 v12, v96, v12, s[26:27]
	v_mul_f32_e32 v9, v13, v175
	v_ashrrev_i32_e32 v13, 31, v12
	v_mul_f32_e32 v10, v28, v176
	v_mul_f32_e32 v11, v29, v177
	v_cvt_pk_bf16_f32 v8, v8, v9
	v_cvt_pk_bf16_f32 v9, v10, v11
	ds_write_b64 v21, v[8:9] offset:240
	v_lshlrev_b64 v[12:13], 8, v[12:13]
	flat_load_dwordx4 v[8:11], v[36:37] offset:1792
	flat_load_dwordx4 v[48:51], v[36:37] offset:1920
	v_lshl_add_u64 v[12:13], s[12:13], 0, v[12:13]
	v_lshl_add_u64 v[28:29], v[12:13], 0, v[184:185]
	flat_load_dwordx4 v[52:55], v[28:29]
	flat_load_dwordx4 v[56:59], v[28:29] offset:16
	v_pk_mul_f32 v[12:13], v[42:43], v[20:21] op_sel_hi:[1,0]
	v_pk_mul_f32 v[42:43], v[44:45], v[20:21] op_sel_hi:[1,0]
	s_waitcnt vmcnt(0) lgkmcnt(0)
	v_mov_b32_e32 v44, v8
	v_mov_b32_e32 v45, v48
	v_mov_b32_e32 v48, v9
	v_mov_b32_e32 v8, v10
	v_mov_b32_e32 v9, v50
	v_mov_b32_e32 v50, v11
	v_pk_mul_f32 v[10:11], v[12:13], v[44:45]
	v_pk_mul_f32 v[12:13], v[42:43], v[48:49]
	v_pk_mul_f32 v[8:9], v[14:15], v[8:9]
	v_pk_mul_f32 v[14:15], v[40:41], v[50:51]
	v_pk_mul_f32 v[40:41], v[10:11], v[52:53]
	v_pk_mul_f32 v[42:43], v[12:13], v[54:55]
	v_pk_mul_f32 v[44:45], v[8:9], v[56:57]
	v_pk_mul_f32 v[48:49], v[14:15], v[58:59]
	v_pk_mul_f32 v[10:11], v[10:11], v[52:53] op_sel:[1,0] op_sel_hi:[0,1]
	v_pk_mul_f32 v[12:13], v[12:13], v[54:55] op_sel:[1,0] op_sel_hi:[0,1]
	v_pk_mul_f32 v[8:9], v[8:9], v[56:57] op_sel:[1,0] op_sel_hi:[0,1]
	v_pk_mul_f32 v[14:15], v[14:15], v[58:59] op_sel:[1,0] op_sel_hi:[0,1]
	v_sub_f32_e32 v33, v40, v41
	v_sub_f32_e32 v35, v42, v43
	v_sub_f32_e32 v40, v44, v45
	v_sub_f32_e32 v41, v48, v49
	v_add_f32_e32 v10, v10, v11
	v_add_f32_e32 v11, v12, v13
	v_add_f32_e32 v12, v8, v9
	v_cvt_pk_bf16_f32 v8, v33, v35
	v_cvt_pk_bf16_f32 v9, v40, v41
	v_add_f32_e32 v13, v14, v15
	ds_write_b64 v21, v[8:9] offset:256
	v_cvt_pk_bf16_f32 v8, v10, v11
	v_cvt_pk_bf16_f32 v9, v12, v13
	ds_write_b64 v21, v[8:9] offset:320
	flat_load_dwordx4 v[8:11], v[36:37] offset:1824
	flat_load_dwordx4 v[12:15], v[36:37] offset:1952
	flat_load_dwordx4 v[40:43], v[28:29] offset:64
	flat_load_dwordx4 v[48:51], v[28:29] offset:80
	v_and_b32_e32 v33, 63, v100
	v_mul_lo_u16_e32 v35, 43, v33
	v_or_b32_e32 v47, 0xc0, v33
	v_or_b32_e32 v52, 0x1c0, v33
	v_or_b32_e32 v53, 0x280, v33
	v_or_b32_e32 v54, 0x240, v33
	v_or_b32_e32 v55, 0x2c0, v33
	v_lshrrev_b16_e32 v35, 10, v35
	v_mul_lo_u16_e32 v56, 0xab, v47
	v_mul_u32_u24_e32 v60, 0xaab, v52
	v_mul_u32_u24_e32 v62, 0xaab, v54
	v_mul_u32_u24_e32 v63, 0xaab, v53
	v_mul_u32_u24_e32 v64, 0xaab, v55
	v_lshrrev_b16_e32 v56, 12, v56
	v_mul_u32_u24_e32 v65, 0x190, v35
	v_lshrrev_b32_e32 v71, 16, v63
	s_waitcnt vmcnt(0) lgkmcnt(0)
	v_mov_b32_e32 v44, v8
	v_mov_b32_e32 v45, v12
	v_mov_b32_e32 v12, v9
	v_mov_b32_e32 v8, v10
	v_mov_b32_e32 v9, v14
	v_mov_b32_e32 v14, v11
	v_pk_mul_f32 v[6:7], v[6:7], v[44:45]
	v_pk_mul_f32 v[4:5], v[4:5], v[12:13]
	v_pk_mul_f32 v[0:1], v[0:1], v[8:9]
	v_pk_mul_f32 v[2:3], v[2:3], v[14:15]
	v_pk_mul_f32 v[8:9], v[6:7], v[40:41]
	v_pk_mul_f32 v[10:11], v[4:5], v[42:43]
	v_pk_mul_f32 v[12:13], v[0:1], v[48:49]
	v_pk_mul_f32 v[14:15], v[2:3], v[50:51]
	v_pk_mul_f32 v[4:5], v[4:5], v[42:43] op_sel:[1,0] op_sel_hi:[0,1]
	v_pk_mul_f32 v[0:1], v[0:1], v[48:49] op_sel:[1,0] op_sel_hi:[0,1]
	v_pk_mul_f32 v[6:7], v[6:7], v[40:41] op_sel:[1,0] op_sel_hi:[0,1]
	v_pk_mul_f32 v[2:3], v[2:3], v[50:51] op_sel:[1,0] op_sel_hi:[0,1]
	v_sub_f32_e32 v8, v8, v9
	v_sub_f32_e32 v9, v10, v11
	v_sub_f32_e32 v10, v12, v13
	v_sub_f32_e32 v11, v14, v15
	v_add_f32_e32 v4, v4, v5
	v_add_f32_e32 v5, v0, v1
	v_cvt_pk_bf16_f32 v0, v8, v9
	v_cvt_pk_bf16_f32 v1, v10, v11
	v_add_f32_e32 v6, v6, v7
	v_add_f32_e32 v2, v2, v3
	ds_write_b64 v21, v[0:1] offset:272
	v_cvt_pk_bf16_f32 v0, v6, v4
	v_cvt_pk_bf16_f32 v1, v5, v2
	ds_write_b64 v21, v[0:1] offset:336
	flat_load_dwordx4 v[12:15], v[36:37] offset:1856
	flat_load_dwordx4 v[8:11], v[36:37] offset:1984
	flat_load_dwordx4 v[0:3], v[28:29] offset:128
	flat_load_dwordx4 v[4:7], v[28:29] offset:144
	v_or_b32_e32 v44, 64, v33
	v_or_b32_e32 v45, 0x80, v33
	v_mul_lo_u16_e32 v42, 43, v44
	v_mul_lo_u16_e32 v43, 0xab, v45
	v_lshrrev_b16_e32 v66, 10, v42
	v_lshrrev_b16_e32 v67, 12, v43
	v_or_b32_e32 v48, 0x100, v33
	v_or_b32_e32 v49, 0x180, v33
	v_or_b32_e32 v50, 0x140, v33
	v_or_b32_e32 v51, 0x200, v33
	v_mul_u32_u24_e32 v57, 0xaab, v48
	v_mul_u32_u24_e32 v58, 0xaab, v50
	v_mul_u32_u24_e32 v59, 0xaab, v49
	v_mul_u32_u24_e32 v61, 0xaab, v51
	v_mad_i32_i24 v33, v35, s58, v33
	v_lshrrev_b32_e32 v57, 16, v57
	v_lshrrev_b32_e32 v68, 16, v58
	v_lshrrev_b32_e32 v69, 16, v59
	v_perm_b32 v58, v59, v58, s44
	v_lshrrev_b32_e32 v59, 16, v60
	v_lshrrev_b32_e32 v70, 16, v61
	v_perm_b32 v60, v61, v60, s44
	v_lshrrev_b32_e32 v61, 16, v62
	v_perm_b32 v62, v63, v62, s44
	v_lshrrev_b32_e32 v63, 16, v64
	v_lshlrev_b32_e32 v64, 4, v33
	v_mul_u32_u24_e32 v35, 0x300, v35
	v_lshlrev_b32_e32 v184, 1, v35
	v_mov_b32_e32 v35, v30
	v_mov_b64_e32 v[40:41], s[14:15]
	v_mad_i64_i32 v[40:41], s[2:3], v99, s39, v[40:41]
	v_lshl_add_u64 v[40:41], v[40:41], 0, s[22:23]
	v_mad_i32_i24 v55, v63, s58, v55
	v_lshlrev_b32_e32 v80, 4, v55
	s_waitcnt vmcnt(0) lgkmcnt(0)
; #define LDSP(T) __attribute__((address_space(3))) T*
; template <int NCH, int STRIDE> DEV void slab_flush(char* slab, u16* grow0, int gstride, int lane) {
;   asm volatile("s_waitcnt lgkmcnt(0)" ::: "memory");
; #pragma unroll
;   for (int i = 0; i < NCH / 2; ++i) {
;     const int q = i * 64 + lane, row = q / NCH, cc = q - row * NCH;
;     const u32x4 v = *(LDSP(const u32x4))(slab + row * STRIDE + cc * 16);
;     *reinterpret_cast<u32x4*>(grow0 + (long)row * gstride + cc * 8) = v;
;   }
; DEV void epi_uq(f32x16 (&acc)[1][6], const Params& P, int layer, int batch, int m0, int head, int wid, int r32, int hi, char* lds) {
;     ...
;   for (int r4 = 0; r4 < 4; ++r4) {
;     const int i = r4 * 8 + hi * 4;
;     const float4 g1 = *reinterpret_cast<const float4*>(g + 128 + i), g2 = *reinterpret_cast<const float4*>(g + 160 + i);
;     const float4 cs01 = *reinterpret_cast<const float4*>(rp + i), cs23 = *reinterpret_cast<const float4*>(rp + i + 2);
;     const float x1[4] = {acc[0][4][r4 * 4] * inv * g1.x, acc[0][4][r4 * 4 + 1] * inv * g1.y, acc[0][4][r4 * 4 + 2] * inv * g1.z, acc[0][4][r4 * 4 + 3] * inv * g1.w};
;     const float x2[4] = {acc[0][5][r4 * 4] * inv * g2.x, acc[0][5][r4 * 4 + 1] * inv * g2.y, acc[0][5][r4 * 4 + 2] * inv * g2.z, acc[0][5][r4 * 4 + 3] * inv * g2.w};
;     const float cc[4] = {cs01.x, cs01.z, cs23.x, cs23.z}, sn[4] = {cs01.y, cs01.w, cs23.y, cs23.w};
;     st4lds(dst, 128 + i, x1[0] * cc[0] - x2[0] * sn[0], x1[1] * cc[1] - x2[1] * sn[1], x1[2] * cc[2] - x2[2] * sn[2], x1[3] * cc[3] - x2[3] * sn[3]);
;     st4lds(dst, 160 + i, x1[0] * sn[0] + x2[0] * cc[0], x1[1] * sn[1] + x2[1] * cc[1], x1[2] * sn[2] + x2[2] * cc[2], x1[3] * sn[3] + x2[3] * cc[3]);
;   }
;   slab_flush<24, 400>(slab, WS{P.ws}.QB() + (long)(m0 + wid * 32) * 768 + head * 192, 768, hi * 32 + r32);
	v_mov_b32_e32 v42, v12
	v_mov_b32_e32 v43, v8
	v_mov_b32_e32 v8, v13
	v_mov_b32_e32 v12, v14
	v_mov_b32_e32 v13, v10
	v_mov_b32_e32 v10, v15
	v_pk_mul_f32 v[14:15], v[38:39], v[42:43]
	v_pk_mul_f32 v[8:9], v[24:25], v[8:9]
	v_pk_mul_f32 v[12:13], v[22:23], v[12:13]
	v_pk_mul_f32 v[10:11], v[26:27], v[10:11]
	v_pk_mul_f32 v[22:23], v[14:15], v[0:1]
	v_pk_mul_f32 v[24:25], v[8:9], v[2:3]
	v_pk_mul_f32 v[26:27], v[12:13], v[4:5]
	v_pk_mul_f32 v[38:39], v[10:11], v[6:7]
	v_pk_mul_f32 v[0:1], v[14:15], v[0:1] op_sel:[1,0] op_sel_hi:[0,1]
	v_pk_mul_f32 v[2:3], v[8:9], v[2:3] op_sel:[1,0] op_sel_hi:[0,1]
	v_pk_mul_f32 v[4:5], v[12:13], v[4:5] op_sel:[1,0] op_sel_hi:[0,1]
	v_pk_mul_f32 v[6:7], v[10:11], v[6:7] op_sel:[1,0] op_sel_hi:[0,1]
	v_sub_f32_e32 v8, v22, v23
	v_sub_f32_e32 v9, v24, v25
	v_sub_f32_e32 v10, v26, v27
	v_sub_f32_e32 v11, v38, v39
	v_add_f32_e32 v12, v0, v1
	v_cvt_pk_bf16_f32 v0, v8, v9
	v_cvt_pk_bf16_f32 v1, v10, v11
	v_add_f32_e32 v2, v2, v3
	v_add_f32_e32 v3, v4, v5
	v_add_f32_e32 v4, v6, v7
	ds_write_b64 v21, v[0:1] offset:288
	v_cvt_pk_bf16_f32 v0, v12, v2
	v_cvt_pk_bf16_f32 v1, v3, v4
	ds_write_b64 v21, v[0:1] offset:352
	flat_load_dwordx4 v[0:3], v[36:37] offset:1888
	flat_load_dwordx4 v[4:7], v[36:37] offset:2016
	flat_load_dwordx4 v[8:11], v[28:29] offset:192
	flat_load_dwordx4 v[12:15], v[28:29] offset:208
	v_lshlrev_b32_e32 v22, 3, v33
	v_mad_i32_i24 v24, v66, s58, v44
	v_mad_i32_i24 v33, v56, s58, v47
	v_mad_i32_i24 v29, v57, s58, v48
	v_mul_u32_u24_e32 v25, 0x190, v66
	v_mad_i32_i24 v26, v67, s58, v45
	v_mul_u32_u24_e32 v27, 0x190, v67
	v_mul_u32_u24_e32 v45, 0x300, v67
	v_mul_u32_u24_e32 v39, 0x190, v57
	v_pk_mul_lo_u16 v42, v58, s37 op_sel_hi:[1,0]
	v_mad_i32_i24 v43, v69, s58, v49
	v_mad_i32_i24 v44, v59, s58, v52
	v_mad_i32_i24 v52, v71, s58, v53
	v_add3_u32 v53, v46, v65, v64
	v_lshlrev_b32_e32 v64, 4, v24
	v_lshlrev_b32_e32 v67, 4, v33
	v_lshlrev_b32_e32 v28, 3, v33
	v_lshlrev_b32_e32 v33, 4, v29
	v_mul_u32_u24_e32 v37, 0x190, v56
	v_mul_u32_u24_e32 v47, 0x300, v56
	v_mul_u32_u24_e32 v56, 0x300, v57
	v_mad_i32_i24 v38, v68, s58, v50
	v_mul_u32_u24_e32 v57, 0x300, v68
	v_pk_mul_lo_u16 v48, v60, s37 op_sel_hi:[1,0]
	v_mad_i32_i24 v49, v70, s58, v51
	v_mul_u32_u24_e32 v60, 0x300, v70
	v_mad_i32_i24 v50, v61, s58, v54
	v_mul_u32_u24_e32 v54, 0x300, v61
	v_mul_u32_u24_e32 v61, 0x300, v71
	v_and_b32_e32 v68, 0xfff0, v42
	v_lshrrev_b32_e32 v70, 16, v42
	v_lshlrev_b32_e32 v71, 4, v43
	v_lshlrev_b32_e32 v42, 3, v43
	v_add3_u32 v43, v46, v25, v64
	v_add3_u32 v64, v46, v39, v33
	v_mov_b32_e32 v33, v31
	v_pk_mul_f32 v[30:31], v[34:35], v[20:21] op_sel_hi:[1,0]
	v_pk_mul_f32 v[32:33], v[32:33], v[20:21] op_sel_hi:[1,0]
	v_ashrrev_i32_e32 v23, 31, v22
	v_mul_u32_u24_e32 v66, 0x300, v66
	v_lshlrev_b32_e32 v24, 3, v24
	v_ashrrev_i32_e32 v25, 31, v24
	v_lshlrev_b32_e32 v65, 4, v26
	v_and_b32_e32 v72, 0xfff0, v48
	v_lshrrev_b32_e32 v74, 16, v48
	v_lshlrev_b32_e32 v75, 4, v49
	v_lshlrev_b32_e32 v48, 3, v49
	v_add3_u32 v49, v46, v27, v65
	v_lshlrev_b32_e32 v26, 3, v26
	v_ashrrev_i32_e32 v27, 31, v26
	v_pk_mul_lo_u16 v51, v62, s37 op_sel_hi:[1,0]
	v_lshlrev_b32_e32 v36, 3, v29
	v_and_b32_e32 v76, 0xfff0, v51
	v_lshrrev_b32_e32 v78, 16, v51
	v_add3_u32 v51, v46, v37, v67
	v_ashrrev_i32_e32 v29, 31, v28
	v_ashrrev_i32_e32 v37, 31, v36
	v_mul_u32_u24_e32 v58, 0x300, v69
	v_lshlrev_b32_e32 v69, 4, v38
	v_add3_u32 v65, v46, v68, v69
	v_lshlrev_b32_e32 v38, 3, v38
	v_ashrrev_i32_e32 v39, 31, v38
	v_lshlrev_b32_e32 v73, 4, v44
	v_mul_u32_u24_e32 v59, 0x300, v59
	v_lshlrev_b32_e32 v44, 3, v44
	v_lshlrev_b32_e32 v77, 4, v50
	v_lshlrev_b32_e32 v50, 3, v50
	v_lshlrev_b32_e32 v79, 4, v52
	v_lshlrev_b32_e32 v52, 3, v52
	v_mul_u32_u24_e32 v62, 0x190, v63
	v_mul_u32_u24_e32 v63, 0x300, v63
	s_waitcnt vmcnt(0) lgkmcnt(0)
; #define LDSP(T) __attribute__((address_space(3))) T*
; template <int NCH, int STRIDE> DEV void slab_flush(char* slab, u16* grow0, int gstride, int lane) {
;   asm volatile("s_waitcnt lgkmcnt(0)" ::: "memory");
; #pragma unroll
;   for (int i = 0; i < NCH / 2; ++i) {
;     const int q = i * 64 + lane, row = q / NCH, cc = q - row * NCH;
;     const u32x4 v = *(LDSP(const u32x4))(slab + row * STRIDE + cc * 16);
;     *reinterpret_cast<u32x4*>(grow0 + (long)row * gstride + cc * 8) = v;
;   }
;   asm volatile("s_waitcnt lgkmcnt(0)" ::: "memory");
; }
; DEV void epi_uq(f32x16 (&acc)[1][6], const Params& P, int layer, int batch, int m0, int head, int wid, int r32, int hi, char* lds) {
;     ...
;     st4lds(dst, 128 + i, x1[0] * cc[0] - x2[0] * sn[0], x1[1] * cc[1] - x2[1] * sn[1], x1[2] * cc[2] - x2[2] * sn[2], x1[3] * cc[3] - x2[3] * sn[3]);
;     st4lds(dst, 160 + i, x1[0] * sn[0] + x2[0] * cc[0], x1[1] * sn[1] + x2[1] * cc[1], x1[2] * sn[2] + x2[2] * cc[2], x1[3] * sn[3] + x2[3] * cc[3]);
;   }
;   slab_flush<24, 400>(slab, WS{P.ws}.QB() + (long)(m0 + wid * 32) * 768 + head * 192, 768, hi * 32 + r32);
	v_mov_b32_e32 v34, v0
	v_mov_b32_e32 v35, v4
	v_mov_b32_e32 v4, v1
	v_mov_b32_e32 v0, v2
	v_mov_b32_e32 v1, v6
	v_mov_b32_e32 v6, v3
	v_pk_mul_f32 v[2:3], v[16:17], v[34:35]
	v_pk_mul_f32 v[4:5], v[18:19], v[4:5]
	v_pk_mul_f32 v[0:1], v[30:31], v[0:1]
	v_pk_mul_f32 v[6:7], v[32:33], v[6:7]
	v_pk_mul_f32 v[16:17], v[2:3], v[8:9]
	v_pk_mul_f32 v[18:19], v[4:5], v[10:11]
	v_pk_mul_f32 v[30:31], v[0:1], v[12:13]
	v_pk_mul_f32 v[32:33], v[6:7], v[14:15]
	v_pk_mul_f32 v[2:3], v[2:3], v[8:9] op_sel:[1,0] op_sel_hi:[0,1]
	v_pk_mul_f32 v[4:5], v[4:5], v[10:11] op_sel:[1,0] op_sel_hi:[0,1]
	v_pk_mul_f32 v[0:1], v[0:1], v[12:13] op_sel:[1,0] op_sel_hi:[0,1]
	v_pk_mul_f32 v[6:7], v[6:7], v[14:15] op_sel:[1,0] op_sel_hi:[0,1]
	v_sub_f32_e32 v8, v16, v17
	v_sub_f32_e32 v9, v18, v19
	v_sub_f32_e32 v10, v30, v31
	v_sub_f32_e32 v11, v32, v33
	v_add_f32_e32 v2, v2, v3
	v_add_f32_e32 v3, v4, v5
	v_add_f32_e32 v4, v0, v1
	v_cvt_pk_bf16_f32 v0, v8, v9
	v_cvt_pk_bf16_f32 v1, v10, v11
	v_add_f32_e32 v5, v6, v7
	ds_write_b64 v21, v[0:1] offset:304
	v_cvt_pk_bf16_f32 v0, v2, v3
	v_cvt_pk_bf16_f32 v1, v4, v5
	ds_write_b64 v21, v[0:1] offset:368
	s_waitcnt lgkmcnt(0)
	ds_read_b128 v[0:3], v53
	v_lshl_add_u64 v[4:5], v[40:41], 0, v[184:185]
	v_lshl_add_u64 v[4:5], v[22:23], 1, v[4:5]
	v_lshlrev_b32_e32 v184, 1, v66
	v_add3_u32 v6, v46, v70, v71
	s_waitcnt lgkmcnt(0)
	flat_store_dwordx4 v[4:5], v[0:3]
	ds_read_b128 v[0:3], v43
	v_lshl_add_u64 v[4:5], v[40:41], 0, v[184:185]
	v_lshl_add_u64 v[4:5], v[24:25], 1, v[4:5]
	v_lshlrev_b32_e32 v184, 1, v45
	v_ashrrev_i32_e32 v43, 31, v42
	s_waitcnt lgkmcnt(0)
	flat_store_dwordx4 v[4:5], v[0:3]
	ds_read_b128 v[0:3], v49
	v_lshl_add_u64 v[4:5], v[40:41], 0, v[184:185]
	v_lshl_add_u64 v[4:5], v[26:27], 1, v[4:5]
	v_lshlrev_b32_e32 v184, 1, v47
	v_add3_u32 v7, v46, v72, v73
	s_waitcnt lgkmcnt(0)
	flat_store_dwordx4 v[4:5], v[0:3]
	ds_read_b128 v[0:3], v51
	v_lshl_add_u64 v[4:5], v[40:41], 0, v[184:185]
	v_lshl_add_u64 v[4:5], v[28:29], 1, v[4:5]
	v_lshlrev_b32_e32 v184, 1, v56
	v_ashrrev_i32_e32 v45, 31, v44
	s_waitcnt lgkmcnt(0)
	flat_store_dwordx4 v[4:5], v[0:3]
	ds_read_b128 v[0:3], v64
	v_lshl_add_u64 v[4:5], v[40:41], 0, v[184:185]
	v_lshl_add_u64 v[4:5], v[36:37], 1, v[4:5]
	v_lshlrev_b32_e32 v184, 1, v57
	v_add3_u32 v8, v46, v74, v75
	s_waitcnt lgkmcnt(0)
	flat_store_dwordx4 v[4:5], v[0:3]
	ds_read_b128 v[0:3], v65
	v_lshl_add_u64 v[4:5], v[40:41], 0, v[184:185]
	v_lshl_add_u64 v[4:5], v[38:39], 1, v[4:5]
	v_lshlrev_b32_e32 v184, 1, v58
	v_ashrrev_i32_e32 v49, 31, v48
	s_waitcnt lgkmcnt(0)
	flat_store_dwordx4 v[4:5], v[0:3]
	ds_read_b128 v[0:3], v6
	v_lshl_add_u64 v[4:5], v[40:41], 0, v[184:185]
	v_lshl_add_u64 v[4:5], v[42:43], 1, v[4:5]
	v_lshlrev_b32_e32 v184, 1, v59
	v_add3_u32 v6, v46, v76, v77
	s_waitcnt lgkmcnt(0)
	flat_store_dwordx4 v[4:5], v[0:3]
	ds_read_b128 v[0:3], v7
	v_lshl_add_u64 v[4:5], v[40:41], 0, v[184:185]
	v_lshl_add_u64 v[4:5], v[44:45], 1, v[4:5]
	v_lshlrev_b32_e32 v184, 1, v60
	v_ashrrev_i32_e32 v51, 31, v50
	s_waitcnt lgkmcnt(0)
	flat_store_dwordx4 v[4:5], v[0:3]
	ds_read_b128 v[0:3], v8
	v_lshl_add_u64 v[4:5], v[40:41], 0, v[184:185]
	v_lshl_add_u64 v[4:5], v[48:49], 1, v[4:5]
	v_lshlrev_b32_e32 v184, 1, v54
	v_add3_u32 v7, v46, v78, v79
	s_waitcnt lgkmcnt(0)
	flat_store_dwordx4 v[4:5], v[0:3]
	ds_read_b128 v[0:3], v6
	v_lshl_add_u64 v[4:5], v[40:41], 0, v[184:185]
	v_lshl_add_u64 v[4:5], v[50:51], 1, v[4:5]
	v_lshlrev_b32_e32 v184, 1, v61
	v_ashrrev_i32_e32 v53, 31, v52
	s_waitcnt lgkmcnt(0)
	flat_store_dwordx4 v[4:5], v[0:3]
	ds_read_b128 v[0:3], v7
	v_lshl_add_u64 v[4:5], v[40:41], 0, v[184:185]
	v_lshl_add_u64 v[4:5], v[52:53], 1, v[4:5]
	v_add3_u32 v6, v46, v62, v80
	v_lshlrev_b32_e32 v184, 1, v63
	s_waitcnt lgkmcnt(0)
	flat_store_dwordx4 v[4:5], v[0:3]
	ds_read_b128 v[0:3], v6
	v_lshlrev_b32_e32 v6, 3, v55
	v_lshl_add_u64 v[4:5], v[40:41], 0, v[184:185]
	v_ashrrev_i32_e32 v7, 31, v6
	v_lshl_add_u64 v[4:5], v[6:7], 1, v[4:5]
	s_waitcnt lgkmcnt(0)
	flat_store_dwordx4 v[4:5], v[0:3]
	s_waitcnt lgkmcnt(0)
	s_waitcnt lgkmcnt(0)
	s_barrier
	s_cbranch_execnz .LBB0_355
